# bundle7 + more bf16 pack peephole conversions (in-place chains)
# baseline (speedup 1.0000x reference)
.LBB0_182:
	s_or_b64 exec, exec, s[12:13]
	s_waitcnt vmcnt(0)
	ds_write2_b32 v86, v2, v3 offset1:1
	ds_write2_b32 v86, v4, v5 offset0:2 offset1:3
	ds_write2_b32 v96, v6, v7 offset1:1
	ds_write2_b32 v97, v8, v9 offset1:1
	ds_write2_b32 v98, v14, v15 offset1:1
	ds_write2_b32 v99, v16, v17 offset1:1
	ds_write2_b32 v100, v10, v11 offset1:1
	ds_write2_b32 v101, v12, v13 offset1:1
	ds_write2_b32 v102, v22, v23 offset1:1
	ds_write2_b32 v103, v24, v25 offset1:1
	ds_write2_b32 v104, v18, v19 offset1:1
	ds_write2_b32 v105, v20, v21 offset1:1
	ds_write2_b32 v106, v30, v31 offset1:1
	ds_write2_b32 v107, v32, v33 offset1:1
	ds_write2_b32 v108, v26, v27 offset1:1
	ds_write2_b32 v109, v28, v29 offset1:1
	ds_write2_b32 v110, v38, v39 offset1:1
	ds_write2_b32 v111, v40, v41 offset1:1
	ds_write2_b32 v112, v34, v35 offset1:1
	ds_write2_b32 v113, v36, v37 offset1:1
	ds_write2_b32 v114, v46, v47 offset1:1
	ds_write2_b32 v115, v48, v49 offset1:1
	ds_write2_b32 v116, v42, v43 offset1:1
	ds_write2_b32 v117, v44, v45 offset1:1
	ds_write2_b32 v118, v54, v55 offset1:1
	ds_write2_b32 v119, v56, v57 offset1:1
	ds_write2_b32 v120, v50, v51 offset1:1
	ds_write2_b32 v121, v52, v53 offset1:1
	ds_write2_b32 v122, v62, v63 offset1:1
	ds_write2_b32 v123, v64, v65 offset1:1
	ds_write2_b32 v124, v58, v59 offset1:1
	ds_write2_b32 v125, v60, v61 offset1:1
	s_waitcnt lgkmcnt(0)
	s_ashr_i32 s11, s10, 31
	v_add_u32_e32 v4, s8, v87
	v_lshl_add_u64 v[2:3], s[10:11], 1, v[80:81]
	v_cmp_gt_i32_e32 vcc, s89, v4
	s_and_saveexec_b64 s[2:3], vcc
	s_cbranch_execz .LBB0_184
	ds_read2_b32 v[6:7], v126 offset0:4 offset1:69
	ds_read2_b32 v[8:9], v126 offset0:134 offset1:199
	ds_read2_b32 v[14:15], v88 offset1:65
	ds_read2_b32 v[16:17], v88 offset0:130 offset1:195
	v_cmp_gt_i32_e32 vcc, s88, v4
	s_waitcnt lgkmcnt(0)
	v_mov_b32_e32 v12, v7
	v_cndmask_b32_e32 v10, v128, v127, vcc
	v_mov_b32_e32 v13, v9
	v_mov_b32_e32 v7, v8
	v_mov_b32_e32 v8, v15
	v_mov_b32_e32 v9, v17
	v_mov_b32_e32 v15, v16
	v_pk_mul_f32 v[12:13], v[10:11], v[12:13] op_sel_hi:[0,1]
	v_pk_mul_f32 v[6:7], v[10:11], v[6:7] op_sel_hi:[0,1]
	v_pk_mul_f32 v[8:9], v[10:11], v[8:9] op_sel_hi:[0,1]
	v_pk_mul_f32 v[10:11], v[10:11], v[14:15] op_sel_hi:[0,1]
	v_bfe_u32 v1, v10, 16, 1
	v_bfe_u32 v5, v11, 16, 1
	v_add3_u32 v5, v11, v5, s29
	v_add3_u32 v1, v10, v1, s29
	v_bfe_u32 v15, v8, 16, 1
	v_lshrrev_b32_e32 v1, 16, v1
	v_add3_u32 v15, v8, v15, s29
	v_bfe_u32 v14, v9, 16, 1
	v_cvt_pk_bf16_f32 v8, v6, v12
	v_and_or_b32 v6, v15, s31, v1
	v_add_u32_e32 v1, 0xffffea00, v4
	v_cmp_lt_i32_e32 vcc, s19, v4
	v_lshrrev_b32_e32 v5, 16, v5
	v_add3_u32 v14, v9, v14, s29
	v_cndmask_b32_e32 v1, v4, v1, vcc
	v_cvt_pk_bf16_f32 v9, v7, v13
	v_and_or_b32 v7, v14, s31, v5
	v_lshlrev_b32_e32 v5, 1, v1
	v_and_b32_e32 v5, 0xffffff00, v5
	v_cndmask_b32_e32 v10, 0, v129, vcc
	v_and_b32_e32 v1, 0x47, v1
	v_or3_b32 v10, v1, v10, v5
	v_ashrrev_i32_e32 v11, 31, v10
	v_lshlrev_b64 v[10:11], 12, v[10:11]
	v_lshl_add_u64 v[10:11], v[2:3], 0, v[10:11]
	global_store_dwordx4 v[10:11], v[6:9], off
.LBB0_184:
	s_or_b64 exec, exec, s[2:3]
	v_add_u32_e32 v5, 8, v4
	v_cmp_gt_i32_e32 vcc, s89, v5
	s_and_saveexec_b64 s[2:3], vcc
	s_cbranch_execz .LBB0_186
	ds_read2_b32 v[6:7], v126 offset0:12 offset1:77
	ds_read2_b32 v[8:9], v126 offset0:142 offset1:207
	ds_read2_b32 v[14:15], v88 offset0:8 offset1:73
	ds_read2_b32 v[16:17], v88 offset0:138 offset1:203
	v_cmp_gt_i32_e32 vcc, s88, v5
	s_waitcnt lgkmcnt(0)
	v_mov_b32_e32 v12, v7
	v_cndmask_b32_e32 v10, v128, v127, vcc
	v_mov_b32_e32 v13, v9
	v_mov_b32_e32 v7, v8
	v_mov_b32_e32 v8, v15
	v_mov_b32_e32 v9, v17
	v_mov_b32_e32 v15, v16
	v_pk_mul_f32 v[12:13], v[10:11], v[12:13] op_sel_hi:[0,1]
	v_pk_mul_f32 v[6:7], v[10:11], v[6:7] op_sel_hi:[0,1]
	v_pk_mul_f32 v[8:9], v[10:11], v[8:9] op_sel_hi:[0,1]
	v_pk_mul_f32 v[10:11], v[10:11], v[14:15] op_sel_hi:[0,1]
	v_bfe_u32 v1, v10, 16, 1
	v_bfe_u32 v14, v11, 16, 1
	v_add3_u32 v11, v11, v14, s29
	v_add3_u32 v1, v10, v1, s29
	v_bfe_u32 v16, v8, 16, 1
	v_lshrrev_b32_e32 v1, 16, v1
	v_add3_u32 v16, v8, v16, s29
	v_cvt_pk_bf16_f32 v8, v6, v12
	v_and_or_b32 v6, v16, s31, v1
	v_add_u32_e32 v1, 0xffffea08, v4
	v_cmp_lt_i32_e32 vcc, s19, v5
	v_lshrrev_b32_e32 v10, 16, v11
	v_bfe_u32 v15, v9, 16, 1
	v_cndmask_b32_e32 v1, v5, v1, vcc
	v_add3_u32 v15, v9, v15, s29
	v_lshlrev_b32_e32 v5, 1, v1
	v_cvt_pk_bf16_f32 v9, v7, v13
	v_and_or_b32 v7, v15, s31, v10
	v_and_b32_e32 v5, 0xffffff00, v5
	v_cndmask_b32_e32 v10, 0, v129, vcc
	v_and_b32_e32 v1, 0x4f, v1
	v_or3_b32 v10, v1, v10, v5
	v_ashrrev_i32_e32 v11, 31, v10
	v_lshlrev_b64 v[10:11], 12, v[10:11]
	v_lshl_add_u64 v[10:11], v[2:3], 0, v[10:11]
	global_store_dwordx4 v[10:11], v[6:9], off
.LBB0_186:
	s_or_b64 exec, exec, s[2:3]
	v_add_u32_e32 v5, 16, v4
	v_cmp_gt_i32_e32 vcc, s89, v5
	s_and_saveexec_b64 s[2:3], vcc
	s_cbranch_execz .LBB0_188
	ds_read2_b32 v[6:7], v126 offset0:20 offset1:85
	ds_read2_b32 v[8:9], v126 offset0:150 offset1:215
	ds_read2_b32 v[14:15], v88 offset0:16 offset1:81
	ds_read2_b32 v[16:17], v88 offset0:146 offset1:211
	v_cmp_gt_i32_e32 vcc, s88, v5
	s_waitcnt lgkmcnt(0)
	v_mov_b32_e32 v12, v7
	v_cndmask_b32_e32 v10, v128, v127, vcc
	v_mov_b32_e32 v13, v9
	v_mov_b32_e32 v7, v8
	v_mov_b32_e32 v8, v15
	v_mov_b32_e32 v9, v17
	v_mov_b32_e32 v15, v16
	v_pk_mul_f32 v[12:13], v[10:11], v[12:13] op_sel_hi:[0,1]
	v_pk_mul_f32 v[6:7], v[10:11], v[6:7] op_sel_hi:[0,1]
	v_pk_mul_f32 v[8:9], v[10:11], v[8:9] op_sel_hi:[0,1]
	v_pk_mul_f32 v[10:11], v[10:11], v[14:15] op_sel_hi:[0,1]
	v_bfe_u32 v1, v10, 16, 1
	v_bfe_u32 v14, v11, 16, 1
	v_add3_u32 v11, v11, v14, s29
	v_add3_u32 v1, v10, v1, s29
	v_bfe_u32 v16, v8, 16, 1
	v_lshrrev_b32_e32 v1, 16, v1
	v_add3_u32 v16, v8, v16, s29
	v_cvt_pk_bf16_f32 v8, v6, v12
	v_and_or_b32 v6, v16, s31, v1
	v_add_u32_e32 v1, 0xffffea10, v4
	v_cmp_lt_i32_e32 vcc, s19, v5
	v_lshrrev_b32_e32 v10, 16, v11
	v_bfe_u32 v15, v9, 16, 1
	v_cndmask_b32_e32 v1, v5, v1, vcc
	v_add3_u32 v15, v9, v15, s29
	v_lshlrev_b32_e32 v5, 1, v1
	v_cvt_pk_bf16_f32 v9, v7, v13
	v_and_or_b32 v7, v15, s31, v10
	v_and_b32_e32 v5, 0xffffff00, v5
	v_cndmask_b32_e32 v10, 0, v129, vcc
	v_and_b32_e32 v1, 0x57, v1
	v_or3_b32 v10, v1, v10, v5
	v_ashrrev_i32_e32 v11, 31, v10
	v_lshlrev_b64 v[10:11], 12, v[10:11]
	v_lshl_add_u64 v[10:11], v[2:3], 0, v[10:11]
	global_store_dwordx4 v[10:11], v[6:9], off
.LBB0_188:
	s_or_b64 exec, exec, s[2:3]
	v_add_u32_e32 v5, 24, v4
	v_cmp_gt_i32_e32 vcc, s89, v5
	s_and_saveexec_b64 s[2:3], vcc
	s_cbranch_execz .LBB0_190
	ds_read2_b32 v[6:7], v126 offset0:28 offset1:93
	ds_read2_b32 v[8:9], v126 offset0:158 offset1:223
	ds_read2_b32 v[14:15], v88 offset0:24 offset1:89
	ds_read2_b32 v[16:17], v88 offset0:154 offset1:219
	v_cmp_gt_i32_e32 vcc, s88, v5
	s_waitcnt lgkmcnt(0)
	v_mov_b32_e32 v12, v7
	v_cndmask_b32_e32 v10, v128, v127, vcc
	v_mov_b32_e32 v13, v9
	v_mov_b32_e32 v7, v8
	v_mov_b32_e32 v8, v15
	v_mov_b32_e32 v9, v17
	v_mov_b32_e32 v15, v16
	v_pk_mul_f32 v[12:13], v[10:11], v[12:13] op_sel_hi:[0,1]
	v_pk_mul_f32 v[6:7], v[10:11], v[6:7] op_sel_hi:[0,1]
	v_pk_mul_f32 v[8:9], v[10:11], v[8:9] op_sel_hi:[0,1]
	v_pk_mul_f32 v[10:11], v[10:11], v[14:15] op_sel_hi:[0,1]
	v_bfe_u32 v1, v10, 16, 1
	v_bfe_u32 v14, v11, 16, 1
	v_add3_u32 v11, v11, v14, s29
	v_add3_u32 v1, v10, v1, s29
	v_bfe_u32 v16, v8, 16, 1
	v_lshrrev_b32_e32 v1, 16, v1
	v_add3_u32 v16, v8, v16, s29
	v_cvt_pk_bf16_f32 v8, v6, v12
	v_and_or_b32 v6, v16, s31, v1
	v_add_u32_e32 v1, 0xffffea18, v4
	v_cmp_lt_i32_e32 vcc, s19, v5
	v_lshrrev_b32_e32 v10, 16, v11
	v_bfe_u32 v15, v9, 16, 1
	v_cndmask_b32_e32 v1, v5, v1, vcc
	v_add3_u32 v15, v9, v15, s29
	v_lshlrev_b32_e32 v5, 1, v1
	v_cvt_pk_bf16_f32 v9, v7, v13
	v_and_or_b32 v7, v15, s31, v10
	v_and_b32_e32 v5, 0xffffff00, v5
	v_cndmask_b32_e32 v10, 0, v129, vcc
	v_and_b32_e32 v1, 0x5f, v1
	v_or3_b32 v10, v1, v10, v5
	v_ashrrev_i32_e32 v11, 31, v10
	v_lshlrev_b64 v[10:11], 12, v[10:11]
	v_lshl_add_u64 v[10:11], v[2:3], 0, v[10:11]
	global_store_dwordx4 v[10:11], v[6:9], off
.LBB0_190:
	s_or_b64 exec, exec, s[2:3]
	v_add_u32_e32 v5, 32, v4
	v_cmp_gt_i32_e32 vcc, s89, v5
	s_and_saveexec_b64 s[2:3], vcc
	s_cbranch_execz .LBB0_192
	ds_read2_b32 v[6:7], v126 offset0:36 offset1:101
	ds_read2_b32 v[8:9], v126 offset0:166 offset1:231
	ds_read2_b32 v[14:15], v88 offset0:32 offset1:97
	ds_read2_b32 v[16:17], v88 offset0:162 offset1:227
	v_cmp_gt_i32_e32 vcc, s88, v5
	s_waitcnt lgkmcnt(0)
	v_mov_b32_e32 v12, v7
	v_cndmask_b32_e32 v10, v128, v127, vcc
	v_mov_b32_e32 v13, v9
	v_mov_b32_e32 v7, v8
	v_mov_b32_e32 v8, v15
	v_mov_b32_e32 v9, v17
	v_mov_b32_e32 v15, v16
	v_pk_mul_f32 v[12:13], v[10:11], v[12:13] op_sel_hi:[0,1]
	v_pk_mul_f32 v[6:7], v[10:11], v[6:7] op_sel_hi:[0,1]
	v_pk_mul_f32 v[8:9], v[10:11], v[8:9] op_sel_hi:[0,1]
	v_pk_mul_f32 v[10:11], v[10:11], v[14:15] op_sel_hi:[0,1]
	v_bfe_u32 v1, v10, 16, 1
	v_bfe_u32 v14, v11, 16, 1
	v_add3_u32 v11, v11, v14, s29
	v_add3_u32 v1, v10, v1, s29
	v_bfe_u32 v16, v8, 16, 1
	v_lshrrev_b32_e32 v1, 16, v1
	v_add3_u32 v16, v8, v16, s29
	v_cvt_pk_bf16_f32 v8, v6, v12
	v_and_or_b32 v6, v16, s31, v1
	v_add_u32_e32 v1, 0xffffea20, v4
	v_cmp_lt_i32_e32 vcc, s19, v5
	v_lshrrev_b32_e32 v10, 16, v11
	v_bfe_u32 v15, v9, 16, 1
	v_cndmask_b32_e32 v1, v5, v1, vcc
	v_add3_u32 v15, v9, v15, s29
	v_lshlrev_b32_e32 v5, 1, v1
	v_cvt_pk_bf16_f32 v9, v7, v13
	v_and_or_b32 v7, v15, s31, v10
	v_and_b32_e32 v5, 0xffffff00, v5
	v_cndmask_b32_e32 v10, 0, v129, vcc
	v_and_b32_e32 v1, 0x67, v1
	v_or3_b32 v10, v1, v10, v5
	v_ashrrev_i32_e32 v11, 31, v10
	v_lshlrev_b64 v[10:11], 12, v[10:11]
	v_lshl_add_u64 v[10:11], v[2:3], 0, v[10:11]
	global_store_dwordx4 v[10:11], v[6:9], off
.LBB0_192:
	s_or_b64 exec, exec, s[2:3]
	v_add_u32_e32 v5, 40, v4
	v_cmp_gt_i32_e32 vcc, s89, v5
	s_and_saveexec_b64 s[2:3], vcc
	s_cbranch_execz .LBB0_194
	ds_read2_b32 v[6:7], v126 offset0:44 offset1:109
	ds_read2_b32 v[8:9], v126 offset0:174 offset1:239
	ds_read2_b32 v[14:15], v88 offset0:40 offset1:105
	ds_read2_b32 v[16:17], v88 offset0:170 offset1:235
	v_cmp_gt_i32_e32 vcc, s88, v5
	s_waitcnt lgkmcnt(0)
	v_mov_b32_e32 v12, v7
	v_cndmask_b32_e32 v10, v128, v127, vcc
	v_mov_b32_e32 v13, v9
	v_mov_b32_e32 v7, v8
	v_mov_b32_e32 v8, v15
	v_mov_b32_e32 v9, v17
	v_mov_b32_e32 v15, v16
	v_pk_mul_f32 v[12:13], v[10:11], v[12:13] op_sel_hi:[0,1]
	v_pk_mul_f32 v[6:7], v[10:11], v[6:7] op_sel_hi:[0,1]
	v_pk_mul_f32 v[8:9], v[10:11], v[8:9] op_sel_hi:[0,1]
	v_pk_mul_f32 v[10:11], v[10:11], v[14:15] op_sel_hi:[0,1]
	v_bfe_u32 v1, v10, 16, 1
	v_bfe_u32 v14, v11, 16, 1
	v_add3_u32 v11, v11, v14, s29
	v_add3_u32 v1, v10, v1, s29
	v_bfe_u32 v16, v8, 16, 1
	v_lshrrev_b32_e32 v1, 16, v1
	v_add3_u32 v16, v8, v16, s29
	v_cvt_pk_bf16_f32 v8, v6, v12
	v_and_or_b32 v6, v16, s31, v1
	v_add_u32_e32 v1, 0xffffea28, v4
	v_cmp_lt_i32_e32 vcc, s19, v5
	v_lshrrev_b32_e32 v10, 16, v11
	v_bfe_u32 v15, v9, 16, 1
	v_cndmask_b32_e32 v1, v5, v1, vcc
	v_add3_u32 v15, v9, v15, s29
	v_lshlrev_b32_e32 v5, 1, v1
	v_cvt_pk_bf16_f32 v9, v7, v13
	v_and_or_b32 v7, v15, s31, v10
	v_and_b32_e32 v5, 0xffffff00, v5
	v_cndmask_b32_e32 v10, 0, v129, vcc
	v_and_b32_e32 v1, 0x6f, v1
	v_or3_b32 v10, v1, v10, v5
	v_ashrrev_i32_e32 v11, 31, v10
	v_lshlrev_b64 v[10:11], 12, v[10:11]
	v_lshl_add_u64 v[10:11], v[2:3], 0, v[10:11]
	global_store_dwordx4 v[10:11], v[6:9], off
.LBB0_194:
	s_or_b64 exec, exec, s[2:3]
	v_add_u32_e32 v5, 48, v4
	v_cmp_gt_i32_e32 vcc, s89, v5
	s_and_saveexec_b64 s[2:3], vcc
	s_cbranch_execz .LBB0_196
	ds_read2_b32 v[6:7], v126 offset0:52 offset1:117
	ds_read2_b32 v[8:9], v126 offset0:182 offset1:247
	ds_read2_b32 v[14:15], v88 offset0:48 offset1:113
	ds_read2_b32 v[16:17], v88 offset0:178 offset1:243
	v_cmp_gt_i32_e32 vcc, s88, v5
	s_waitcnt lgkmcnt(0)
	v_mov_b32_e32 v12, v7
	v_cndmask_b32_e32 v10, v128, v127, vcc
	v_mov_b32_e32 v13, v9
	v_mov_b32_e32 v7, v8
	v_mov_b32_e32 v8, v15
	v_mov_b32_e32 v9, v17
	v_mov_b32_e32 v15, v16
	v_pk_mul_f32 v[12:13], v[10:11], v[12:13] op_sel_hi:[0,1]
	v_pk_mul_f32 v[6:7], v[10:11], v[6:7] op_sel_hi:[0,1]
	v_pk_mul_f32 v[8:9], v[10:11], v[8:9] op_sel_hi:[0,1]
	v_pk_mul_f32 v[10:11], v[10:11], v[14:15] op_sel_hi:[0,1]
	v_bfe_u32 v1, v10, 16, 1
	v_bfe_u32 v14, v11, 16, 1
	v_add3_u32 v11, v11, v14, s29
	v_add3_u32 v1, v10, v1, s29
	v_bfe_u32 v16, v8, 16, 1
	v_lshrrev_b32_e32 v1, 16, v1
	v_add3_u32 v16, v8, v16, s29
	v_cvt_pk_bf16_f32 v8, v6, v12
	v_and_or_b32 v6, v16, s31, v1
	v_add_u32_e32 v1, 0xffffea30, v4
	v_cmp_lt_i32_e32 vcc, s19, v5
	v_lshrrev_b32_e32 v10, 16, v11
	v_bfe_u32 v15, v9, 16, 1
	v_cndmask_b32_e32 v1, v5, v1, vcc
	v_add3_u32 v15, v9, v15, s29
	v_lshlrev_b32_e32 v5, 1, v1
	v_cvt_pk_bf16_f32 v9, v7, v13
	v_and_or_b32 v7, v15, s31, v10
	v_and_b32_e32 v5, 0xffffff00, v5
	v_cndmask_b32_e32 v10, 0, v129, vcc
	v_and_b32_e32 v1, 0x77, v1
	v_or3_b32 v10, v1, v10, v5
	v_ashrrev_i32_e32 v11, 31, v10
	v_lshlrev_b64 v[10:11], 12, v[10:11]
	v_lshl_add_u64 v[10:11], v[2:3], 0, v[10:11]
	global_store_dwordx4 v[10:11], v[6:9], off
.LBB0_196:
	s_or_b64 exec, exec, s[2:3]
	v_add_u32_e32 v5, 56, v4
	v_cmp_gt_i32_e32 vcc, s89, v5
	s_and_saveexec_b64 s[2:3], vcc
	s_cbranch_execz .LBB0_9
	ds_read2_b32 v[6:7], v126 offset0:60 offset1:125
	ds_read2_b32 v[8:9], v126 offset0:190 offset1:255
	ds_read2_b32 v[14:15], v88 offset0:56 offset1:121
	ds_read2_b32 v[16:17], v88 offset0:186 offset1:251
	v_cmp_gt_i32_e32 vcc, s88, v5
	s_waitcnt lgkmcnt(0)
	v_mov_b32_e32 v12, v7
	v_cndmask_b32_e32 v10, v128, v127, vcc
	v_mov_b32_e32 v13, v9
	v_mov_b32_e32 v7, v8
	v_mov_b32_e32 v8, v15
	v_mov_b32_e32 v9, v17
	v_mov_b32_e32 v15, v16
	v_pk_mul_f32 v[12:13], v[10:11], v[12:13] op_sel_hi:[0,1]
	v_pk_mul_f32 v[6:7], v[10:11], v[6:7] op_sel_hi:[0,1]
	v_pk_mul_f32 v[8:9], v[10:11], v[8:9] op_sel_hi:[0,1]
	v_pk_mul_f32 v[10:11], v[10:11], v[14:15] op_sel_hi:[0,1]
	v_bfe_u32 v1, v10, 16, 1
	v_bfe_u32 v14, v11, 16, 1
	v_add3_u32 v11, v11, v14, s29
	v_add3_u32 v1, v10, v1, s29
	v_bfe_u32 v16, v8, 16, 1
	v_lshrrev_b32_e32 v1, 16, v1
	v_add3_u32 v16, v8, v16, s29
	v_cvt_pk_bf16_f32 v8, v6, v12
	v_and_or_b32 v6, v16, s31, v1
	v_add_u32_e32 v1, 0xffffea38, v4
	v_cmp_lt_i32_e32 vcc, s19, v5
	v_lshrrev_b32_e32 v10, 16, v11
	v_cndmask_b32_e32 v1, v5, v1, vcc
	v_lshlrev_b32_e32 v4, 1, v1
	v_and_b32_e32 v4, 0xffffff00, v4
	v_cndmask_b32_e32 v5, 0, v129, vcc
	v_and_b32_e32 v1, 0x7f, v1
	v_or3_b32 v4, v1, v5, v4
	v_bfe_u32 v15, v9, 16, 1
	v_ashrrev_i32_e32 v5, 31, v4
	v_add3_u32 v15, v9, v15, s29
	v_lshlrev_b64 v[4:5], 12, v[4:5]
	v_cvt_pk_bf16_f32 v9, v7, v13
	v_and_or_b32 v7, v15, s31, v10
	v_lshl_add_u64 v[2:3], v[2:3], 0, v[4:5]
	global_store_dwordx4 v[2:3], v[6:9], off
	s_branch .LBB0_9

.LBB0_796:
	s_waitcnt vmcnt(0)
	v_pk_mul_f32 v[4:5], v[54:55], v[2:3] op_sel_hi:[1,0]
	v_pk_mul_f32 v[2:3], v[56:57], v[2:3] op_sel_hi:[1,0]
	ds_write2_b32 v116, v4, v5 offset1:1
	ds_write2_b32 v117, v2, v3 offset1:1
	s_waitcnt lgkmcnt(0)
	s_ashr_i32 s7, s6, 31
	v_add_u32_e32 v4, s4, v79
	v_lshl_add_u64 v[2:3], s[6:7], 1, v[70:71]
	v_cmp_gt_i32_e32 vcc, s22, v4
	s_and_saveexec_b64 s[2:3], vcc
	s_cbranch_execz .LBB0_798
	ds_read2_b32 v[6:7], v118 offset0:4 offset1:69
	ds_read2_b32 v[8:9], v118 offset0:134 offset1:199
	ds_read2_b32 v[14:15], v80 offset1:65
	ds_read2_b32 v[16:17], v80 offset0:130 offset1:195
	v_cmp_gt_i32_e32 vcc, s19, v4
	s_waitcnt lgkmcnt(3)
	v_mov_b32_e32 v12, v7
	v_cndmask_b32_e32 v10, v119, v120, vcc
	s_waitcnt lgkmcnt(2)
	v_mov_b32_e32 v13, v9
	v_mov_b32_e32 v7, v8
	s_waitcnt lgkmcnt(1)
	v_mov_b32_e32 v8, v15
	s_waitcnt lgkmcnt(0)
	v_mov_b32_e32 v9, v17
	v_mov_b32_e32 v15, v16
	v_pk_mul_f32 v[12:13], v[10:11], v[12:13] op_sel_hi:[0,1]
	v_pk_mul_f32 v[6:7], v[10:11], v[6:7] op_sel_hi:[0,1]
	v_pk_mul_f32 v[8:9], v[10:11], v[8:9] op_sel_hi:[0,1]
	v_pk_mul_f32 v[10:11], v[10:11], v[14:15] op_sel_hi:[0,1]
	v_bfe_u32 v1, v10, 16, 1
	v_bfe_u32 v5, v11, 16, 1
	v_add3_u32 v5, v11, v5, s17
	v_add3_u32 v1, v10, v1, s17
	v_bfe_u32 v15, v8, 16, 1
	v_lshrrev_b32_e32 v1, 16, v1
	v_add3_u32 v15, v8, v15, s17
	v_bfe_u32 v14, v9, 16, 1
	v_cvt_pk_bf16_f32 v8, v6, v12
	v_and_or_b32 v6, v15, s18, v1
	v_add_u32_e32 v1, 0xffffea00, v4
	v_cmp_lt_i32_e32 vcc, s16, v4
	v_lshrrev_b32_e32 v5, 16, v5
	v_add3_u32 v14, v9, v14, s17
	v_cndmask_b32_e32 v1, v4, v1, vcc
	v_cvt_pk_bf16_f32 v9, v7, v13
	v_and_or_b32 v7, v14, s18, v5
	v_lshlrev_b32_e32 v5, 1, v1
	v_and_b32_e32 v5, 0xffffff00, v5
	v_cndmask_b32_e32 v10, 0, v121, vcc
	v_and_b32_e32 v1, 0x47, v1
	v_or3_b32 v10, v1, v10, v5
	v_ashrrev_i32_e32 v11, 31, v10
	v_lshlrev_b64 v[10:11], 12, v[10:11]
	v_lshl_add_u64 v[10:11], v[2:3], 0, v[10:11]
	global_store_dwordx4 v[10:11], v[6:9], off
.LBB0_798:
	s_or_b64 exec, exec, s[2:3]
	v_add_u32_e32 v5, 8, v4
	v_cmp_gt_i32_e32 vcc, s22, v5
	s_and_saveexec_b64 s[2:3], vcc
	s_cbranch_execz .LBB0_800
	ds_read2_b32 v[6:7], v118 offset0:12 offset1:77
	ds_read2_b32 v[8:9], v118 offset0:142 offset1:207
	ds_read2_b32 v[14:15], v80 offset0:8 offset1:73
	ds_read2_b32 v[16:17], v80 offset0:138 offset1:203
	v_cmp_gt_i32_e32 vcc, s19, v5
	s_waitcnt lgkmcnt(3)
	v_mov_b32_e32 v12, v7
	v_cndmask_b32_e32 v10, v119, v120, vcc
	s_waitcnt lgkmcnt(2)
	v_mov_b32_e32 v13, v9
	v_mov_b32_e32 v7, v8
	s_waitcnt lgkmcnt(1)
	v_mov_b32_e32 v8, v15
	s_waitcnt lgkmcnt(0)
	v_mov_b32_e32 v9, v17
	v_mov_b32_e32 v15, v16
	v_pk_mul_f32 v[12:13], v[10:11], v[12:13] op_sel_hi:[0,1]
	v_pk_mul_f32 v[6:7], v[10:11], v[6:7] op_sel_hi:[0,1]
	v_pk_mul_f32 v[8:9], v[10:11], v[8:9] op_sel_hi:[0,1]
	v_pk_mul_f32 v[10:11], v[10:11], v[14:15] op_sel_hi:[0,1]
	v_bfe_u32 v1, v10, 16, 1
	v_bfe_u32 v14, v11, 16, 1
	v_add3_u32 v11, v11, v14, s17
	v_add3_u32 v1, v10, v1, s17
	v_bfe_u32 v16, v8, 16, 1
	v_lshrrev_b32_e32 v1, 16, v1
	v_add3_u32 v16, v8, v16, s17
	v_cvt_pk_bf16_f32 v8, v6, v12
	v_and_or_b32 v6, v16, s18, v1
	v_add_u32_e32 v1, 0xffffea08, v4
	v_cmp_lt_i32_e32 vcc, s16, v5
	v_lshrrev_b32_e32 v10, 16, v11
	v_bfe_u32 v15, v9, 16, 1
	v_cndmask_b32_e32 v1, v5, v1, vcc
	v_add3_u32 v15, v9, v15, s17
	v_lshlrev_b32_e32 v5, 1, v1
	v_cvt_pk_bf16_f32 v9, v7, v13
	v_and_or_b32 v7, v15, s18, v10
	v_and_b32_e32 v5, 0xffffff00, v5
	v_cndmask_b32_e32 v10, 0, v121, vcc
	v_and_b32_e32 v1, 0x4f, v1
	v_or3_b32 v10, v1, v10, v5
	v_ashrrev_i32_e32 v11, 31, v10
	v_lshlrev_b64 v[10:11], 12, v[10:11]
	v_lshl_add_u64 v[10:11], v[2:3], 0, v[10:11]
	global_store_dwordx4 v[10:11], v[6:9], off
.LBB0_800:
	s_or_b64 exec, exec, s[2:3]
	v_add_u32_e32 v5, 16, v4
	v_cmp_gt_i32_e32 vcc, s22, v5
	s_and_saveexec_b64 s[2:3], vcc
	s_cbranch_execz .LBB0_802
	ds_read2_b32 v[6:7], v118 offset0:20 offset1:85
	ds_read2_b32 v[8:9], v118 offset0:150 offset1:215
	ds_read2_b32 v[14:15], v80 offset0:16 offset1:81
	ds_read2_b32 v[16:17], v80 offset0:146 offset1:211
	v_cmp_gt_i32_e32 vcc, s19, v5
	s_waitcnt lgkmcnt(3)
	v_mov_b32_e32 v12, v7
	v_cndmask_b32_e32 v10, v119, v120, vcc
	s_waitcnt lgkmcnt(2)
	v_mov_b32_e32 v13, v9
	v_mov_b32_e32 v7, v8
	s_waitcnt lgkmcnt(1)
	v_mov_b32_e32 v8, v15
	s_waitcnt lgkmcnt(0)
	v_mov_b32_e32 v9, v17
	v_mov_b32_e32 v15, v16
	v_pk_mul_f32 v[12:13], v[10:11], v[12:13] op_sel_hi:[0,1]
	v_pk_mul_f32 v[6:7], v[10:11], v[6:7] op_sel_hi:[0,1]
	v_pk_mul_f32 v[8:9], v[10:11], v[8:9] op_sel_hi:[0,1]
	v_pk_mul_f32 v[10:11], v[10:11], v[14:15] op_sel_hi:[0,1]
	v_bfe_u32 v1, v10, 16, 1
	v_bfe_u32 v14, v11, 16, 1
	v_add3_u32 v11, v11, v14, s17
	v_add3_u32 v1, v10, v1, s17
	v_bfe_u32 v16, v8, 16, 1
	v_lshrrev_b32_e32 v1, 16, v1
	v_add3_u32 v16, v8, v16, s17
	v_cvt_pk_bf16_f32 v8, v6, v12
	v_and_or_b32 v6, v16, s18, v1
	v_add_u32_e32 v1, 0xffffea10, v4
	v_cmp_lt_i32_e32 vcc, s16, v5
	v_lshrrev_b32_e32 v10, 16, v11
	v_bfe_u32 v15, v9, 16, 1
	v_cndmask_b32_e32 v1, v5, v1, vcc
	v_add3_u32 v15, v9, v15, s17
	v_lshlrev_b32_e32 v5, 1, v1
	v_cvt_pk_bf16_f32 v9, v7, v13
	v_and_or_b32 v7, v15, s18, v10
	v_and_b32_e32 v5, 0xffffff00, v5
	v_cndmask_b32_e32 v10, 0, v121, vcc
	v_and_b32_e32 v1, 0x57, v1
	v_or3_b32 v10, v1, v10, v5
	v_ashrrev_i32_e32 v11, 31, v10
	v_lshlrev_b64 v[10:11], 12, v[10:11]
	v_lshl_add_u64 v[10:11], v[2:3], 0, v[10:11]
	global_store_dwordx4 v[10:11], v[6:9], off
.LBB0_802:
	s_or_b64 exec, exec, s[2:3]
	v_add_u32_e32 v5, 24, v4
	v_cmp_gt_i32_e32 vcc, s22, v5
	s_and_saveexec_b64 s[2:3], vcc
	s_cbranch_execz .LBB0_804
	ds_read2_b32 v[6:7], v118 offset0:28 offset1:93
	ds_read2_b32 v[8:9], v118 offset0:158 offset1:223
	ds_read2_b32 v[14:15], v80 offset0:24 offset1:89
	ds_read2_b32 v[16:17], v80 offset0:154 offset1:219
	v_cmp_gt_i32_e32 vcc, s19, v5
	s_waitcnt lgkmcnt(3)
	v_mov_b32_e32 v12, v7
	v_cndmask_b32_e32 v10, v119, v120, vcc
	s_waitcnt lgkmcnt(2)
	v_mov_b32_e32 v13, v9
	v_mov_b32_e32 v7, v8
	s_waitcnt lgkmcnt(1)
	v_mov_b32_e32 v8, v15
	s_waitcnt lgkmcnt(0)
	v_mov_b32_e32 v9, v17
	v_mov_b32_e32 v15, v16
	v_pk_mul_f32 v[12:13], v[10:11], v[12:13] op_sel_hi:[0,1]
	v_pk_mul_f32 v[6:7], v[10:11], v[6:7] op_sel_hi:[0,1]
	v_pk_mul_f32 v[8:9], v[10:11], v[8:9] op_sel_hi:[0,1]
	v_pk_mul_f32 v[10:11], v[10:11], v[14:15] op_sel_hi:[0,1]
	v_bfe_u32 v1, v10, 16, 1
	v_bfe_u32 v14, v11, 16, 1
	v_add3_u32 v11, v11, v14, s17
	v_add3_u32 v1, v10, v1, s17
	v_bfe_u32 v16, v8, 16, 1
	v_lshrrev_b32_e32 v1, 16, v1
	v_add3_u32 v16, v8, v16, s17
	v_cvt_pk_bf16_f32 v8, v6, v12
	v_and_or_b32 v6, v16, s18, v1
	v_add_u32_e32 v1, 0xffffea18, v4
	v_cmp_lt_i32_e32 vcc, s16, v5
	v_lshrrev_b32_e32 v10, 16, v11
	v_bfe_u32 v15, v9, 16, 1
	v_cndmask_b32_e32 v1, v5, v1, vcc
	v_add3_u32 v15, v9, v15, s17
	v_lshlrev_b32_e32 v5, 1, v1
	v_cvt_pk_bf16_f32 v9, v7, v13
	v_and_or_b32 v7, v15, s18, v10
	v_and_b32_e32 v5, 0xffffff00, v5
	v_cndmask_b32_e32 v10, 0, v121, vcc
	v_and_b32_e32 v1, 0x5f, v1
	v_or3_b32 v10, v1, v10, v5
	v_ashrrev_i32_e32 v11, 31, v10
	v_lshlrev_b64 v[10:11], 12, v[10:11]
	v_lshl_add_u64 v[10:11], v[2:3], 0, v[10:11]
	global_store_dwordx4 v[10:11], v[6:9], off
.LBB0_804:
	s_or_b64 exec, exec, s[2:3]
	v_add_u32_e32 v5, 32, v4
	v_cmp_gt_i32_e32 vcc, s22, v5
	s_and_saveexec_b64 s[2:3], vcc
	s_cbranch_execz .LBB0_806
	ds_read2_b32 v[6:7], v118 offset0:36 offset1:101
	ds_read2_b32 v[8:9], v118 offset0:166 offset1:231
	ds_read2_b32 v[14:15], v80 offset0:32 offset1:97
	ds_read2_b32 v[16:17], v80 offset0:162 offset1:227
	v_cmp_gt_i32_e32 vcc, s19, v5
	s_waitcnt lgkmcnt(3)
	v_mov_b32_e32 v12, v7
	v_cndmask_b32_e32 v10, v119, v120, vcc
	s_waitcnt lgkmcnt(2)
	v_mov_b32_e32 v13, v9
	v_mov_b32_e32 v7, v8
	s_waitcnt lgkmcnt(1)
	v_mov_b32_e32 v8, v15
	s_waitcnt lgkmcnt(0)
	v_mov_b32_e32 v9, v17
	v_mov_b32_e32 v15, v16
	v_pk_mul_f32 v[12:13], v[10:11], v[12:13] op_sel_hi:[0,1]
	v_pk_mul_f32 v[6:7], v[10:11], v[6:7] op_sel_hi:[0,1]
	v_pk_mul_f32 v[8:9], v[10:11], v[8:9] op_sel_hi:[0,1]
	v_pk_mul_f32 v[10:11], v[10:11], v[14:15] op_sel_hi:[0,1]
	v_bfe_u32 v1, v10, 16, 1
	v_bfe_u32 v14, v11, 16, 1
	v_add3_u32 v11, v11, v14, s17
	v_add3_u32 v1, v10, v1, s17
	v_bfe_u32 v16, v8, 16, 1
	v_lshrrev_b32_e32 v1, 16, v1
	v_add3_u32 v16, v8, v16, s17
	v_cvt_pk_bf16_f32 v8, v6, v12
	v_and_or_b32 v6, v16, s18, v1
	v_add_u32_e32 v1, 0xffffea20, v4
	v_cmp_lt_i32_e32 vcc, s16, v5
	v_lshrrev_b32_e32 v10, 16, v11
	v_bfe_u32 v15, v9, 16, 1
	v_cndmask_b32_e32 v1, v5, v1, vcc
	v_add3_u32 v15, v9, v15, s17
	v_lshlrev_b32_e32 v5, 1, v1
	v_cvt_pk_bf16_f32 v9, v7, v13
	v_and_or_b32 v7, v15, s18, v10
	v_and_b32_e32 v5, 0xffffff00, v5
	v_cndmask_b32_e32 v10, 0, v121, vcc
	v_and_b32_e32 v1, 0x67, v1
	v_or3_b32 v10, v1, v10, v5
	v_ashrrev_i32_e32 v11, 31, v10
	v_lshlrev_b64 v[10:11], 12, v[10:11]
	v_lshl_add_u64 v[10:11], v[2:3], 0, v[10:11]
	global_store_dwordx4 v[10:11], v[6:9], off
.LBB0_806:
	s_or_b64 exec, exec, s[2:3]
	v_add_u32_e32 v5, 40, v4
	v_cmp_gt_i32_e32 vcc, s22, v5
	s_and_saveexec_b64 s[2:3], vcc
	s_cbranch_execz .LBB0_808
	ds_read2_b32 v[6:7], v118 offset0:44 offset1:109
	ds_read2_b32 v[8:9], v118 offset0:174 offset1:239
	ds_read2_b32 v[14:15], v80 offset0:40 offset1:105
	ds_read2_b32 v[16:17], v80 offset0:170 offset1:235
	v_cmp_gt_i32_e32 vcc, s19, v5
	s_waitcnt lgkmcnt(3)
	v_mov_b32_e32 v12, v7
	v_cndmask_b32_e32 v10, v119, v120, vcc
	s_waitcnt lgkmcnt(2)
	v_mov_b32_e32 v13, v9
	v_mov_b32_e32 v7, v8
	s_waitcnt lgkmcnt(1)
	v_mov_b32_e32 v8, v15
	s_waitcnt lgkmcnt(0)
	v_mov_b32_e32 v9, v17
	v_mov_b32_e32 v15, v16
	v_pk_mul_f32 v[12:13], v[10:11], v[12:13] op_sel_hi:[0,1]
	v_pk_mul_f32 v[6:7], v[10:11], v[6:7] op_sel_hi:[0,1]
	v_pk_mul_f32 v[8:9], v[10:11], v[8:9] op_sel_hi:[0,1]
	v_pk_mul_f32 v[10:11], v[10:11], v[14:15] op_sel_hi:[0,1]
	v_bfe_u32 v1, v10, 16, 1
	v_bfe_u32 v14, v11, 16, 1
	v_add3_u32 v11, v11, v14, s17
	v_add3_u32 v1, v10, v1, s17
	v_bfe_u32 v16, v8, 16, 1
	v_lshrrev_b32_e32 v1, 16, v1
	v_add3_u32 v16, v8, v16, s17
	v_cvt_pk_bf16_f32 v8, v6, v12
	v_and_or_b32 v6, v16, s18, v1
	v_add_u32_e32 v1, 0xffffea28, v4
	v_cmp_lt_i32_e32 vcc, s16, v5
	v_lshrrev_b32_e32 v10, 16, v11
	v_bfe_u32 v15, v9, 16, 1
	v_cndmask_b32_e32 v1, v5, v1, vcc
	v_add3_u32 v15, v9, v15, s17
	v_lshlrev_b32_e32 v5, 1, v1
	v_cvt_pk_bf16_f32 v9, v7, v13
	v_and_or_b32 v7, v15, s18, v10
	v_and_b32_e32 v5, 0xffffff00, v5
	v_cndmask_b32_e32 v10, 0, v121, vcc
	v_and_b32_e32 v1, 0x6f, v1
	v_or3_b32 v10, v1, v10, v5
	v_ashrrev_i32_e32 v11, 31, v10
	v_lshlrev_b64 v[10:11], 12, v[10:11]
	v_lshl_add_u64 v[10:11], v[2:3], 0, v[10:11]
	global_store_dwordx4 v[10:11], v[6:9], off
.LBB0_808:
	s_or_b64 exec, exec, s[2:3]
	v_add_u32_e32 v5, 48, v4
	v_cmp_gt_i32_e32 vcc, s22, v5
	s_and_saveexec_b64 s[2:3], vcc
	s_cbranch_execz .LBB0_810
	ds_read2_b32 v[6:7], v118 offset0:52 offset1:117
	ds_read2_b32 v[8:9], v118 offset0:182 offset1:247
	ds_read2_b32 v[14:15], v80 offset0:48 offset1:113
	ds_read2_b32 v[16:17], v80 offset0:178 offset1:243
	v_cmp_gt_i32_e32 vcc, s19, v5
	s_waitcnt lgkmcnt(3)
	v_mov_b32_e32 v12, v7
	v_cndmask_b32_e32 v10, v119, v120, vcc
	s_waitcnt lgkmcnt(2)
	v_mov_b32_e32 v13, v9
	v_mov_b32_e32 v7, v8
	s_waitcnt lgkmcnt(1)
	v_mov_b32_e32 v8, v15
	s_waitcnt lgkmcnt(0)
	v_mov_b32_e32 v9, v17
	v_mov_b32_e32 v15, v16
	v_pk_mul_f32 v[12:13], v[10:11], v[12:13] op_sel_hi:[0,1]
	v_pk_mul_f32 v[6:7], v[10:11], v[6:7] op_sel_hi:[0,1]
	v_pk_mul_f32 v[8:9], v[10:11], v[8:9] op_sel_hi:[0,1]
	v_pk_mul_f32 v[10:11], v[10:11], v[14:15] op_sel_hi:[0,1]
	v_bfe_u32 v1, v10, 16, 1
	v_bfe_u32 v14, v11, 16, 1
	v_add3_u32 v11, v11, v14, s17
	v_add3_u32 v1, v10, v1, s17
	v_bfe_u32 v16, v8, 16, 1
	v_lshrrev_b32_e32 v1, 16, v1
	v_add3_u32 v16, v8, v16, s17
	v_cvt_pk_bf16_f32 v8, v6, v12
	v_and_or_b32 v6, v16, s18, v1
	v_add_u32_e32 v1, 0xffffea30, v4
	v_cmp_lt_i32_e32 vcc, s16, v5
	v_lshrrev_b32_e32 v10, 16, v11
	v_bfe_u32 v15, v9, 16, 1
	v_cndmask_b32_e32 v1, v5, v1, vcc
	v_add3_u32 v15, v9, v15, s17
	v_lshlrev_b32_e32 v5, 1, v1
	v_cvt_pk_bf16_f32 v9, v7, v13
	v_and_or_b32 v7, v15, s18, v10
	v_and_b32_e32 v5, 0xffffff00, v5
	v_cndmask_b32_e32 v10, 0, v121, vcc
	v_and_b32_e32 v1, 0x77, v1
	v_or3_b32 v10, v1, v10, v5
	v_ashrrev_i32_e32 v11, 31, v10
	v_lshlrev_b64 v[10:11], 12, v[10:11]
	v_lshl_add_u64 v[10:11], v[2:3], 0, v[10:11]
	global_store_dwordx4 v[10:11], v[6:9], off
.LBB0_810:
	s_or_b64 exec, exec, s[2:3]
	v_add_u32_e32 v5, 56, v4
	v_cmp_gt_i32_e32 vcc, s22, v5
	s_and_saveexec_b64 s[2:3], vcc
	s_cbranch_execz .LBB0_735
	ds_read2_b32 v[6:7], v118 offset0:60 offset1:125
	ds_read2_b32 v[8:9], v118 offset0:190 offset1:255
	ds_read2_b32 v[14:15], v80 offset0:56 offset1:121
	ds_read2_b32 v[16:17], v80 offset0:186 offset1:251
	v_cmp_gt_i32_e32 vcc, s19, v5
	s_waitcnt lgkmcnt(3)
	v_mov_b32_e32 v12, v7
	v_cndmask_b32_e32 v10, v119, v120, vcc
	s_waitcnt lgkmcnt(2)
	v_mov_b32_e32 v13, v9
	v_mov_b32_e32 v7, v8
	s_waitcnt lgkmcnt(1)
	v_mov_b32_e32 v8, v15
	s_waitcnt lgkmcnt(0)
	v_mov_b32_e32 v9, v17
	v_mov_b32_e32 v15, v16
	v_pk_mul_f32 v[12:13], v[10:11], v[12:13] op_sel_hi:[0,1]
	v_pk_mul_f32 v[6:7], v[10:11], v[6:7] op_sel_hi:[0,1]
	v_pk_mul_f32 v[8:9], v[10:11], v[8:9] op_sel_hi:[0,1]
	v_pk_mul_f32 v[10:11], v[10:11], v[14:15] op_sel_hi:[0,1]
	v_bfe_u32 v1, v10, 16, 1
	v_bfe_u32 v14, v11, 16, 1
	v_add3_u32 v11, v11, v14, s17
	v_add3_u32 v1, v10, v1, s17
	v_bfe_u32 v16, v8, 16, 1
	v_lshrrev_b32_e32 v1, 16, v1
	v_add3_u32 v16, v8, v16, s17
	v_cvt_pk_bf16_f32 v8, v6, v12
	v_and_or_b32 v6, v16, s18, v1
	v_add_u32_e32 v1, 0xffffea38, v4
	v_cmp_lt_i32_e32 vcc, s16, v5
	v_lshrrev_b32_e32 v10, 16, v11
	v_cndmask_b32_e32 v1, v5, v1, vcc
	v_lshlrev_b32_e32 v4, 1, v1
	v_and_b32_e32 v4, 0xffffff00, v4
	v_cndmask_b32_e32 v5, 0, v121, vcc
	v_and_b32_e32 v1, 0x7f, v1
	v_or3_b32 v4, v1, v5, v4
	v_bfe_u32 v15, v9, 16, 1
	v_ashrrev_i32_e32 v5, 31, v4
	v_add3_u32 v15, v9, v15, s17
	v_lshlrev_b64 v[4:5], 12, v[4:5]
	v_cvt_pk_bf16_f32 v9, v7, v13
	v_and_or_b32 v7, v15, s18, v10
	v_lshl_add_u64 v[2:3], v[2:3], 0, v[4:5]
	global_store_dwordx4 v[2:3], v[6:9], off
	s_branch .LBB0_735

.LBB0_877:
	s_or_b64 exec, exec, s[8:9]
	v_add_u32_e32 v1, 8, v172
	v_min_u32_e32 v1, v1, v170
	v_cvt_f32_ubyte0_e32 v1, v1
	v_div_scale_f32 v10, s[8:9], v1, v1, 1.0
	v_rcp_f32_e32 v11, v10
	v_div_scale_f32 v12, vcc, 1.0, v1, 1.0
	v_mov_b32_e32 v15, v61
	v_fma_f32 v13, -v10, v11, 1.0
	v_fmac_f32_e32 v11, v13, v11
	v_mul_f32_e32 v13, v12, v11
	v_fma_f32 v14, -v10, v13, v12
	v_fmac_f32_e32 v13, v14, v11
	v_fma_f32 v10, -v10, v13, v12
	v_div_fmas_f32 v10, v10, v11, v13
	v_div_fixup_f32 v10, v10, v1, 1.0
	v_mov_b32_e32 v12, v45
	v_mov_b32_e32 v13, v69
	v_mov_b32_e32 v14, v43
	v_mov_b32_e32 v45, v68
	v_mov_b32_e32 v43, v60
	v_mov_b32_e32 v16, v7
	v_mov_b32_e32 v18, v3
	v_mov_b32_e32 v7, v8
	v_mov_b32_e32 v3, v4
	v_pk_fma_f32 v[12:13], v[10:11], v[12:13], v[14:15] op_sel_hi:[0,1,1] neg_lo:[0,0,1] neg_hi:[0,0,1]
	v_pk_fma_f32 v[14:15], v[10:11], v[44:45], v[42:43] op_sel_hi:[0,1,1] neg_lo:[0,0,1] neg_hi:[0,0,1]
	v_mov_b32_e32 v17, v9
	v_mov_b32_e32 v19, v5
	v_pk_fma_f32 v[2:3], v[10:11], v[6:7], v[2:3] op_sel_hi:[0,1,1] neg_lo:[0,0,1] neg_hi:[0,0,1]
	v_pk_fma_f32 v[16:17], v[10:11], v[16:17], v[18:19] op_sel_hi:[0,1,1] neg_lo:[0,0,1] neg_hi:[0,0,1]
	v_bfe_u32 v1, v3, 16, 1
	v_add3_u32 v1, v3, v1, s17
	v_bfe_u32 v3, v12, 16, 1
	v_bfe_u32 v6, v14, 16, 1
	v_add3_u32 v3, v12, v3, s17
	v_add3_u32 v6, v14, v6, s17
	v_lshrrev_b32_e32 v9, 16, v3
	v_bfe_u32 v8, v17, 16, 1
	v_cvt_pk_bf16_f32 v4, v16, v2
	v_and_or_b32 v2, v6, s16, v9
	v_or_b32_e32 v6, 7, v171
	v_add3_u32 v8, v17, v8, s17
	v_cvt_pk_bf16_f32 v3, v13, v15
	v_ashrrev_i32_e32 v7, 31, v6
	v_add_u32_e32 v178, s30, v178
	v_lshrrev_b32_e32 v5, 16, v8
	v_lshlrev_b64 v[6:7], 12, v[6:7]
	v_cmp_lt_i32_e32 vcc, s18, v178
	v_and_or_b32 v5, v1, s16, v5
	v_lshl_add_u64 v[6:7], v[92:93], 0, v[6:7]
	s_or_b64 s[10:11], vcc, s[10:11]
	global_store_dwordx4 v[6:7], v[2:5], off
	s_andn2_b64 exec, exec, s[10:11]
	s_cbranch_execz .LBB0_1132

.LBB0_936:
	s_or_b64 exec, exec, s[8:9]
	v_or_b32_e32 v1, 1, v172
	v_min_u32_e32 v1, v1, v170
	v_cvt_f32_ubyte0_e32 v1, v1
	v_div_scale_f32 v30, s[8:9], v1, v1, 1.0
	v_rcp_f32_e32 v31, v30
	v_div_scale_f32 v32, vcc, 1.0, v1, 1.0
	v_mov_b32_e32 v49, v129
	v_fma_f32 v33, -v30, v31, 1.0
	v_fmac_f32_e32 v31, v33, v31
	v_mul_f32_e32 v33, v32, v31
	v_fma_f32 v48, -v30, v33, v32
	v_fmac_f32_e32 v33, v48, v31
	v_fma_f32 v30, -v30, v33, v32
	v_div_fmas_f32 v30, v30, v31, v33
	v_div_fixup_f32 v30, v30, v1, 1.0
	v_mov_b32_e32 v32, v167
	v_mov_b32_e32 v33, v169
	v_mov_b32_e32 v48, v127
	v_pk_fma_f32 v[32:33], v[30:31], v[32:33], v[48:49] op_sel_hi:[0,1,1] neg_lo:[0,0,1] neg_hi:[0,0,1]
	v_mov_b32_e32 v167, v168
	v_mov_b32_e32 v48, v126
	v_mov_b32_e32 v49, v128
	v_pk_fma_f32 v[48:49], v[30:31], v[166:167], v[48:49] op_sel_hi:[0,1,1] neg_lo:[0,0,1] neg_hi:[0,0,1]
	v_mov_b32_e32 v166, v163
	v_mov_b32_e32 v167, v165
	v_mov_b32_e32 v168, v131
	v_mov_b32_e32 v169, v133
	v_mov_b32_e32 v163, v164
	v_mov_b32_e32 v164, v130
	v_mov_b32_e32 v165, v132
	v_pk_fma_f32 v[166:167], v[30:31], v[166:167], v[168:169] op_sel_hi:[0,1,1] neg_lo:[0,0,1] neg_hi:[0,0,1]
	v_pk_fma_f32 v[30:31], v[30:31], v[162:163], v[164:165] op_sel_hi:[0,1,1] neg_lo:[0,0,1] neg_hi:[0,0,1]
	v_bfe_u32 v1, v31, 16, 1
	v_bfe_u32 v163, v49, 16, 1
	v_bfe_u32 v164, v48, 16, 1
	v_add3_u32 v49, v49, v163, s17
	v_add3_u32 v1, v31, v1, s17
	v_bfe_u32 v31, v32, 16, 1
	v_bfe_u32 v162, v33, 16, 1
	v_add3_u32 v48, v48, v164, s17
	v_bfe_u32 v164, v167, 16, 1
	v_add3_u32 v33, v33, v162, s17
	v_add3_u32 v31, v32, v31, s17
	v_add3_u32 v164, v167, v164, s17
	v_lshrrev_b32_e32 v162, 16, v31
	v_lshrrev_b32_e32 v31, 16, v33
	v_lshrrev_b32_e32 v33, 16, v164
	v_cvt_pk_bf16_f32 v32, v166, v30
	v_and_or_b32 v31, v49, s16, v31
	v_and_or_b32 v30, v48, s16, v162
	v_lshlrev_b64 v[48:49], 12, v[94:95]
	v_and_or_b32 v33, v1, s16, v33
	v_lshl_add_u64 v[48:49], v[92:93], 0, v[48:49]
	global_store_dwordx4 v[48:49], v[30:33], off
	s_nop 0
	s_nop 1
	v_and_b32_e32 v30, 0xffff0000, v26
	v_lshlrev_b32_e32 v31, 16, v26
	v_pk_add_f32 v[32:33], v[30:31], 0 op_sel_hi:[1,0]
	v_and_b32_e32 v26, 0xffff0000, v27
	v_lshlrev_b32_e32 v27, 16, v27
	v_pk_add_f32 v[164:165], v[32:33], v[126:127]
	v_pk_add_f32 v[32:33], v[26:27], 0 op_sel_hi:[1,0]
	s_nop 0
	v_pk_add_f32 v[166:167], v[32:33], v[128:129]
	v_and_b32_e32 v32, 0xffff0000, v28
	v_lshlrev_b32_e32 v33, 16, v28
	v_and_b32_e32 v28, 0xffff0000, v29
	v_lshlrev_b32_e32 v29, 16, v29
	v_pk_add_f32 v[48:49], v[32:33], 0 op_sel_hi:[1,0]
	v_pk_add_f32 v[162:163], v[28:29], 0 op_sel_hi:[1,0]
	v_pk_add_f32 v[48:49], v[48:49], v[130:131]
	v_pk_add_f32 v[162:163], v[162:163], v[132:133]
	s_and_saveexec_b64 s[8:9], s[2:3]
	s_cbranch_execnz .LBB0_1040
	s_or_b64 exec, exec, s[8:9]
	s_and_saveexec_b64 s[8:9], s[2:3]
	s_cbranch_execnz .LBB0_1041
